# P7 entry: the three write-after-read dependency words are read in one round trip (fast path) before the serial wait loops
# speedup vs baseline: 1.0052x; 1.0011x over previous
.LBB0_1266:
	s_cmp_lt_i32 s4, 8
	s_cselect_b64 s[0:1], -1, 0
	s_and_b64 s[10:11], s[0:1], s[6:7]
	v_readlane_b32 s0, v236, 6
	v_readlane_b32 s1, v236, 7
	s_and_b64 s[0:1], s[10:11], s[0:1]
	s_andn2_b64 vcc, exec, s[0:1]
	s_cbranch_vccnz .LBB0_1293
	s_and_saveexec_b64 s[0:1], s[22:23]
	s_cbranch_execz .LBB0_1292
	s_add_u32 s3, s72, 0x91000
	v_readlane_b32 s5, v236, 8
	s_addc_u32 s4, s73, 0
	s_lshl_b32 s98, s5, 5
	s_and_b32 s98, s98, 0x7c0
	s_add_u32 s98, s3, s98
	s_addc_u32 s99, s4, 0
	v_mov_b32_e32 v238, 0x5000
	global_load_dword v239, v238, s[98:99] sc1
	s_mul_i32 s100, s5, 6
	s_and_b32 s98, s100, 0x1f0
	s_lshl_b32 s98, s98, 2
	s_add_u32 s98, s3, s98
	s_addc_u32 s99, s4, 0
	v_mov_b32_e32 v240, 0x5800
	global_load_dword v241, v240, s[98:99] sc1
	s_addk_i32 s100, 0x204
	s_and_b32 s100, s100, 0x7f0
	s_lshl_b32 s100, s100, 2
	s_add_u32 s98, s3, s100
	s_addc_u32 s99, s4, 0
	global_load_dword v242, v238, s[98:99] sc1
	s_waitcnt vmcnt(0)
	v_min3_u32 v239, v239, v241, v242
	v_cmp_lt_u32_e32 vcc, 3, v239
	s_cbranch_vccnz .LBB0_1292
	s_lshl_b32 s5, s5, 5
	s_and_b32 s5, s5, 0x7c0
	s_add_u32 s5, s3, s5
	s_addc_u32 s7, s4, 0
	s_add_u32 s6, s5, 0x5000
	s_addc_u32 s7, s7, 0
	s_mov_b32 s5, 0x400001
	v_mov_b32_e32 v1, 0
	s_branch .LBB0_1270
